# softmax row sum with packed f32 adds (7 v_pk_add + 1 v_add instead of 16 v_add)
# speedup vs baseline: 1.0607x; 1.0056x over previous
; DI unsigned pk2(float lo, float hi) { f32x2 v = {lo, hi}; return __builtin_bit_cast(unsigned, __builtin_convertvector(v, bf2_t)); }
; #define MFMA32(a, b, c) __builtin_amdgcn_mfma_f32_32x32x16_bf16((a), (b), (c), 0, 0, 0)
; DI void attn_unit(const Params& p, int b, int h, int qb, LAS unsigned char* lds, int tid, int lane, int wave) {
;     ...
;             const float muse = (mrow == -INFINITY) ? 0.f : mrow;
;             float ps = 0.f;
; #pragma unroll
;             for (int j = 0; j < 16; ++j) { s[j] = __builtin_amdgcn_exp2f(s[j] - muse); ps += s[j]; }
;             lrow += ps;
; #pragma unroll
;             for (int ks = 0; ks < 2; ++ks) {
;                 u32x4 pw; pw.x = pk2(s[8 * ks], s[8 * ks + 1]); pw.y = pk2(s[8 * ks + 2], s[8 * ks + 3]); pw.z = pk2(s[8 * ks + 4], s[8 * ks + 5]); pw.w = pk2(s[8 * ks + 6], s[8 * ks + 7]);
;                 const bf16x8 pf = __builtin_bit_cast(bf16x8, pw);
;                 __builtin_amdgcn_s_setprio(1);
; #pragma unroll
;                 for (int blk = 0; blk < 4; ++blk) o[blk] = MFMA32(vf[ks][blk], pf, o[blk]);
;                 __builtin_amdgcn_s_setprio(0);
;             }
.LBB0_427:
	v_exp_f32_e32 v66, v66
	v_exp_f32_e32 v67, v67
	v_exp_f32_e32 v68, v68
	v_exp_f32_e32 v69, v69
	v_exp_f32_e32 v70, v70
	v_exp_f32_e32 v71, v71
	v_exp_f32_e32 v72, v72
	v_exp_f32_e32 v73, v73
	v_exp_f32_e32 v74, v74
	v_exp_f32_e32 v75, v75
	v_exp_f32_e32 v76, v76
	v_exp_f32_e32 v77, v77
	v_exp_f32_e32 v78, v78
	v_exp_f32_e32 v79, v79
	v_exp_f32_e32 v80, v80
	v_exp_f32_e32 v81, v81
	v_pk_add_f32 v[194:195], v[66:67], v[68:69]
	v_pk_add_f32 v[194:195], v[194:195], v[70:71]
	v_pk_add_f32 v[194:195], v[194:195], v[72:73]
	v_pk_add_f32 v[194:195], v[194:195], v[74:75]
	v_pk_add_f32 v[194:195], v[194:195], v[76:77]
	v_pk_add_f32 v[194:195], v[194:195], v[78:79]
	v_pk_add_f32 v[194:195], v[194:195], v[80:81]
	v_add_f32_e32 v194, v194, v195
	v_cvt_pk_bf16_f32 v66, v66, v67
	v_cvt_pk_bf16_f32 v67, v68, v69
	v_cvt_pk_bf16_f32 v68, v70, v71
	v_cvt_pk_bf16_f32 v69, v72, v73
	s_setprio 1
	s_waitcnt lgkmcnt(7)
	v_mfma_f32_32x32x16_bf16 v[50:65], v[166:169], v[66:69], v[50:65]
	s_waitcnt lgkmcnt(5)
	v_mfma_f32_32x32x16_bf16 v[34:49], v[170:173], v[66:69], v[34:49]
	s_waitcnt lgkmcnt(4)
	v_mfma_f32_32x32x16_bf16 v[18:33], v[178:181], v[66:69], v[18:33]
	s_waitcnt lgkmcnt(3)
	v_mfma_f32_32x32x16_bf16 v[2:17], v[174:177], v[66:69], v[2:17]
	s_setprio 0
	v_cvt_pk_bf16_f32 v66, v74, v75
	v_cvt_pk_bf16_f32 v67, v76, v77
	v_cvt_pk_bf16_f32 v68, v78, v79
	v_cvt_pk_bf16_f32 v69, v80, v81
	s_setprio 1
	s_nop 0
	v_mfma_f32_32x32x16_bf16 v[50:65], v[150:153], v[66:69], v[50:65]
	s_waitcnt lgkmcnt(2)
	v_mfma_f32_32x32x16_bf16 v[34:49], v[162:165], v[66:69], v[34:49]
	s_waitcnt lgkmcnt(1)
	v_mfma_f32_32x32x16_bf16 v[18:33], v[158:161], v[66:69], v[18:33]
	s_waitcnt lgkmcnt(0)
	v_mfma_f32_32x32x16_bf16 v[2:17], v[154:157], v[66:69], v[2:17]
	s_setprio 0
	v_add_f32_e32 v203, v203, v194
